# norm_phase loop: all 20 per-column parameter loads (g, shift, scale for both rows) issued together with the row loads instead of 8 serialized round trips after the reduction
# speedup vs baseline: 1.0096x; 1.0023x over previous
.LBB0_167:
	s_add_i32 s26, s12, 0xffff8000
	s_add_u32 s31, s22, s46
	s_addc_u32 s27, s23, s47
	s_cmp_lt_i32 s12, 0x8000
	s_cselect_b32 s27, s27, 0
	s_cselect_b32 s26, s31, s26
	s_cselect_b32 s31, s19, s21
	s_cselect_b32 s34, s18, s20
	s_lshl_b64 s[26:27], s[26:27], 12
	s_add_u32 s26, s34, s26
	s_addc_u32 s27, s31, s27
	v_lshlrev_b64 v[56:57], 2, v[46:47]
	v_lshl_add_u64 v[2:3], s[26:27], 0, v[56:57]
	global_load_dwordx4 v[30:33], v[2:3], off
	v_lshl_add_u64 v[4:5], s[24:25], 0, v[56:57]
	global_load_dwordx4 v[26:29], v[4:5], off
	global_load_dwordx4 v[22:25], v[2:3], off offset:1024
	global_load_dwordx4 v[18:21], v[4:5], off offset:1024
	global_load_dwordx4 v[14:17], v[2:3], off offset:2048
	global_load_dwordx4 v[10:13], v[4:5], off offset:2048
	global_load_dwordx4 v[6:9], v[2:3], off offset:3072
	s_nop 0
	global_load_dwordx4 v[2:5], v[4:5], off offset:3072
	s_min_i32 s24, s12, 0x8000
	s_ashr_i32 s24, s24, 12
	s_min_i32 s25, s60, 0x8000
	s_ashr_i32 s26, s25, 12
	s_mul_hi_i32 s25, s24, 0x9000
	s_mul_i32 s24, s24, 0x9000
	s_add_u32 s24, s29, s24
	s_addc_u32 s25, s30, s25
	s_add_u32 s58, s24, s48
	s_addc_u32 s59, s25, s49
	s_add_u32 s24, s24, s50
	s_addc_u32 s25, s25, s51
	v_lshl_add_u64 v[58:59], s[58:59], 0, v[56:57]
	v_lshl_add_u64 v[60:61], s[24:25], 0, v[56:57]
	s_mul_hi_i32 s27, s26, 0x9000
	s_mul_i32 s26, s26, 0x9000
	s_add_u32 s26, s29, s26
	s_addc_u32 s27, s30, s27
	s_add_u32 s40, s26, s48
	s_addc_u32 s41, s27, s49
	s_add_u32 s54, s26, s50
	s_addc_u32 s55, s27, s51
	v_lshl_add_u64 v[102:103], s[40:41], 0, v[56:57]
	v_lshl_add_u64 v[104:105], s[54:55], 0, v[56:57]
	global_load_dwordx4 v[138:141], v[48:49], off
	global_load_dwordx4 v[142:145], v[58:59], off
	global_load_dwordx4 v[146:149], v[60:61], off
	global_load_dwordx4 v[106:109], v[102:103], off
	global_load_dwordx4 v[122:125], v[104:105], off
	global_load_dwordx4 v[66:69], v[48:49], off offset:1024
	global_load_dwordx4 v[78:81], v[58:59], off offset:1024
	global_load_dwordx4 v[90:93], v[60:61], off offset:1024
	global_load_dwordx4 v[110:113], v[102:103], off offset:1024
	global_load_dwordx4 v[126:129], v[104:105], off offset:1024
	global_load_dwordx4 v[70:73], v[48:49], off offset:2048
	global_load_dwordx4 v[82:85], v[58:59], off offset:2048
	global_load_dwordx4 v[94:97], v[60:61], off offset:2048
	global_load_dwordx4 v[114:117], v[102:103], off offset:2048
	global_load_dwordx4 v[130:133], v[104:105], off offset:2048
	global_load_dwordx4 v[74:77], v[48:49], off offset:3072
	global_load_dwordx4 v[86:89], v[58:59], off offset:3072
	global_load_dwordx4 v[98:101], v[60:61], off offset:3072
	global_load_dwordx4 v[118:121], v[102:103], off offset:3072
	global_load_dwordx4 v[134:137], v[104:105], off offset:3072
	s_waitcnt vmcnt(27)
	v_pk_mul_f32 v[34:35], v[32:33], v[32:33]
	v_pk_mul_f32 v[36:37], v[30:31], v[30:31]
	s_waitcnt vmcnt(21)
	v_mul_f32_e32 v0, v6, v6
	v_pk_mov_b32 v[38:39], v[36:37], v[34:35] op_sel:[1,0]
	v_mov_b32_e32 v37, v35
	v_pk_add_f32 v[34:35], v[38:39], v[36:37]
	v_pk_mul_f32 v[36:37], v[28:29], v[28:29]
	v_pk_mul_f32 v[38:39], v[26:27], v[26:27]
	v_pk_add_f32 v[34:35], v[34:35], v[34:35] op_sel:[0,1] op_sel_hi:[1,0]
	v_pk_mov_b32 v[40:41], v[38:39], v[36:37] op_sel:[1,0]
	v_mov_b32_e32 v39, v37
	v_pk_add_f32 v[36:37], v[40:41], v[38:39]
	v_pk_mul_f32 v[38:39], v[24:25], v[24:25]
	v_pk_mul_f32 v[40:41], v[22:23], v[22:23]
	v_mov_b32_e32 v35, v0
	v_pk_mov_b32 v[42:43], v[40:41], v[38:39] op_sel:[1,0]
	v_mov_b32_e32 v41, v39
	v_pk_add_f32 v[38:39], v[42:43], v[40:41]
	v_pk_mul_f32 v[40:41], v[20:21], v[20:21]
	v_pk_mul_f32 v[42:43], v[18:19], v[18:19]
	v_pk_add_f32 v[38:39], v[38:39], v[38:39] op_sel:[0,1] op_sel_hi:[1,0]
	v_pk_mov_b32 v[44:45], v[42:43], v[40:41] op_sel:[1,0]
	v_mov_b32_e32 v43, v41
	v_pk_add_f32 v[40:41], v[44:45], v[42:43]
	v_mul_f32_e32 v42, v7, v7
	v_mov_b32_e32 v39, v42
	v_mul_f32_e32 v0, v15, v15
	v_mul_f32_e32 v43, v8, v8
	v_pk_add_f32 v[34:35], v[34:35], v[38:39]
	v_pk_fma_f32 v[38:39], v[14:15], v[14:15], v[0:1] op_sel_hi:[1,1,0]
	v_mul_f32_e32 v0, v17, v17
	v_mul_f32_e32 v44, v9, v9
	v_mov_b32_e32 v39, v43
	v_pk_fma_f32 v[42:43], v[16:17], v[16:17], v[0:1] op_sel_hi:[1,1,0]
	s_waitcnt vmcnt(20)
	v_mul_f32_e32 v0, v2, v2
	v_mov_b32_e32 v43, v44
	v_pk_add_f32 v[38:39], v[38:39], v[42:43]
	v_mul_f32_e32 v43, v5, v5
	v_pk_add_f32 v[34:35], v[34:35], v[38:39]
	v_mul_f32_e32 v38, v3, v3
	v_add_f32_e32 v42, v34, v35
	v_pk_add_f32 v[34:35], v[36:37], v[36:37] op_sel:[0,1] op_sel_hi:[1,0]
	v_pk_add_f32 v[36:37], v[40:41], v[40:41] op_sel:[0,1] op_sel_hi:[1,0]
	v_mov_b32_e32 v35, v0
	v_mov_b32_e32 v37, v38
	v_mul_f32_e32 v0, v11, v11
	v_mul_f32_e32 v39, v4, v4
	v_pk_add_f32 v[34:35], v[34:35], v[36:37]
	v_pk_fma_f32 v[36:37], v[10:11], v[10:11], v[0:1] op_sel_hi:[1,1,0]
	v_mul_f32_e32 v0, v13, v13
	v_mov_b32_e32 v37, v39
	v_pk_fma_f32 v[38:39], v[12:13], v[12:13], v[0:1] op_sel_hi:[1,1,0]
	s_nop 0
	v_mov_b32_e32 v39, v43
	v_pk_add_f32 v[36:37], v[36:37], v[38:39]
	s_nop 0
	v_pk_add_f32 v[34:35], v[34:35], v[36:37]
	s_nop 0
	v_add_f32_e32 v0, v34, v35
	v_add_f32_dpp v34, v42, v42 quad_perm:[1,0,3,2] row_mask:0xf bank_mask:0xf bound_ctrl:1
	s_nop 0
	v_add_f32_dpp v0, v0, v0 quad_perm:[1,0,3,2] row_mask:0xf bank_mask:0xf bound_ctrl:1
	v_add_f32_dpp v34, v34, v34 quad_perm:[2,3,0,1] row_mask:0xf bank_mask:0xf bound_ctrl:1
	s_nop 0
	v_add_f32_dpp v0, v0, v0 quad_perm:[2,3,0,1] row_mask:0xf bank_mask:0xf bound_ctrl:1
	v_add_f32_dpp v34, v34, v34 row_half_mirror row_mask:0xf bank_mask:0xf bound_ctrl:1
	s_nop 0
	v_add_f32_dpp v0, v0, v0 row_half_mirror row_mask:0xf bank_mask:0xf bound_ctrl:1
	v_add_f32_dpp v34, v34, v34 row_mirror row_mask:0xf bank_mask:0xf bound_ctrl:1
	s_nop 0
	v_readlane_b32 s26, v34, 16
	v_readlane_b32 s27, v34, 48
	v_add_f32_dpp v0, v0, v0 row_mirror row_mask:0xf bank_mask:0xf bound_ctrl:1
	v_readlane_b32 s24, v34, 0
	v_readlane_b32 s25, v34, 32
	v_mov_b32_e32 v34, s26
	v_mov_b32_e32 v35, s27
	v_readlane_b32 s26, v0, 16
	v_readlane_b32 s27, v0, 48
	v_pk_add_f32 v[34:35], s[24:25], v[34:35]
	v_readlane_b32 s24, v0, 0
	v_readlane_b32 s25, v0, 32
	v_mov_b32_e32 v36, s26
	v_mov_b32_e32 v37, s27
	v_pk_add_f32 v[36:37], s[24:25], v[36:37]
	v_mov_b32_e32 v39, v34
	v_mov_b32_e32 v38, v36
	v_mov_b32_e32 v34, v37
	v_pk_add_f32 v[34:35], v[38:39], v[34:35]
	s_mov_b32 s24, 0x3a800000
	v_pk_fma_f32 v[34:35], v[34:35], s[24:25], v[182:183] op_sel_hi:[1,0,0]
	s_nop 0
	v_mul_f32_e32 v0, 0x4b800000, v35
	v_cmp_gt_f32_e64 s[40:41], s66, v35
	s_nop 0
	s_nop 0
	v_cndmask_b32_e64 v0, v35, v0, s[40:41]
	v_rsq_f32_e32 v0, v0
	s_nop 0
	s_nop 0
	s_nop 0
	v_mul_f32_e32 v35, 0x45800000, v0
	v_cmp_gt_f32_e32 vcc, s66, v34
	v_cndmask_b32_e64 v54, v0, v35, s[40:41]
	v_mul_f32_e32 v0, 0x4b800000, v34
	s_nop 0
	v_cndmask_b32_e32 v0, v34, v0, vcc
	s_nop 0
	v_rsq_f32_e32 v0, v0
	s_nop 0
	s_nop 0
	s_nop 0
	s_nop 0
	v_mul_f32_e32 v34, 0x45800000, v0
	s_nop 0
	s_nop 0
	v_cndmask_b32_e32 v52, v0, v34, vcc
	s_cmp_lg_u32 s12, s60
	v_pk_mul_f32 v[30:31], v[30:31], v[54:55] op_sel_hi:[1,0]
	s_cselect_b64 s[52:53], -1, 0
	s_lshl_b64 s[26:27], s[60:61], 11
	v_pk_mul_f32 v[32:33], v[32:33], v[54:55] op_sel_hi:[1,0]
	s_add_u32 s56, s14, s26
	s_addc_u32 s57, s15, s27
	s_cmp_eq_u32 s12, s60
	v_mov_b32_e32 v53, v52
	s_waitcnt vmcnt(17)
	v_pk_mul_f32 v[30:31], v[138:139], v[30:31]
	v_pk_mul_f32 v[32:33], v[140:141], v[32:33]
	v_pk_add_f32 v[42:43], v[146:147], 1.0 op_sel_hi:[1,0]
	v_pk_add_f32 v[44:45], v[148:149], 1.0 op_sel_hi:[1,0]
	v_pk_fma_f32 v[30:31], v[42:43], v[30:31], v[142:143]
	v_pk_fma_f32 v[32:33], v[44:45], v[32:33], v[144:145]
	v_cvt_pk_bf16_f32 v30, v30, v31
	s_nop 0
	v_cvt_pk_bf16_f32 v31, v32, v33
	global_store_dwordx2 v[50:51], v[30:31], off
	s_nop 0
	v_lshl_add_u64 v[30:31], v[46:47], 1, s[56:57]
	s_cbranch_scc1 .LBB0_169
	v_mov_b32_e32 v44, v52
	v_mov_b32_e32 v45, v52
	v_pk_mul_f32 v[28:29], v[28:29], v[44:45]
	v_pk_mul_f32 v[26:27], v[26:27], v[52:53]
	v_pk_mul_f32 v[28:29], v[140:141], v[28:29]
	v_pk_mul_f32 v[26:27], v[138:139], v[26:27]
	s_waitcnt vmcnt(16)
	v_pk_add_f32 v[36:37], v[122:123], 1.0 op_sel_hi:[1,0]
	v_pk_add_f32 v[34:35], v[124:125], 1.0 op_sel_hi:[1,0]
	v_pk_fma_f32 v[26:27], v[26:27], v[36:37], v[106:107]
	v_pk_fma_f32 v[28:29], v[28:29], v[34:35], v[108:109]
	v_cvt_pk_bf16_f32 v26, v26, v27
	s_nop 0
	v_cvt_pk_bf16_f32 v27, v28, v29
	global_store_dwordx2 v[30:31], v[26:27], off
.LBB0_169:
	v_mov_b32_e32 v55, v54
	v_mov_b32_e32 v34, v54
	v_mov_b32_e32 v35, v54
	v_pk_mul_f32 v[22:23], v[22:23], v[54:55]
	v_pk_mul_f32 v[24:25], v[24:25], v[34:35]
	v_cndmask_b32_e64 v0, 0, 1, s[52:53]
	v_cmp_ne_u32_e64 s[40:41], 1, v0
	s_andn2_b64 vcc, exec, s[52:53]
	s_waitcnt vmcnt(13)
	v_pk_mul_f32 v[22:23], v[22:23], v[66:67]
	v_pk_mul_f32 v[24:25], v[24:25], v[68:69]
	v_pk_add_f32 v[44:45], v[90:91], 1.0 op_sel_hi:[1,0]
	v_pk_add_f32 v[36:37], v[92:93], 1.0 op_sel_hi:[1,0]
	v_pk_fma_f32 v[22:23], v[22:23], v[44:45], v[78:79]
	v_pk_fma_f32 v[24:25], v[24:25], v[36:37], v[80:81]
	v_cvt_pk_bf16_f32 v22, v22, v23
	s_nop 0
	v_cvt_pk_bf16_f32 v23, v24, v25
	global_store_dwordx2 v[50:51], v[22:23], off offset:512
	s_cbranch_vccnz .LBB0_171
	v_mov_b32_e32 v36, v52
	v_mov_b32_e32 v37, v52
	v_pk_mul_f32 v[20:21], v[20:21], v[36:37]
	v_pk_mul_f32 v[18:19], v[18:19], v[52:53]
	v_pk_mul_f32 v[20:21], v[20:21], v[68:69]
	v_pk_mul_f32 v[18:19], v[18:19], v[66:67]
	s_waitcnt vmcnt(13)
	v_pk_add_f32 v[28:29], v[126:127], 1.0 op_sel_hi:[1,0]
	v_pk_add_f32 v[26:27], v[128:129], 1.0 op_sel_hi:[1,0]
	v_pk_fma_f32 v[18:19], v[18:19], v[28:29], v[110:111]
	v_pk_fma_f32 v[20:21], v[20:21], v[26:27], v[112:113]
	v_cvt_pk_bf16_f32 v18, v18, v19
	s_nop 0
	v_cvt_pk_bf16_f32 v19, v20, v21
	global_store_dwordx2 v[30:31], v[18:19], off offset:512
.LBB0_171:
	v_pk_mul_f32 v[14:15], v[14:15], v[54:55]
	v_pk_mul_f32 v[16:17], v[16:17], v[34:35]
	s_and_b64 vcc, exec, s[40:41]
	s_movk_i32 s52, 0x11ff
	s_movk_i32 s56, 0x43
	s_movk_i32 s54, 0x5ff
	s_mov_b32 s55, 0x7ffff
	s_waitcnt vmcnt(9)
	v_pk_mul_f32 v[14:15], v[14:15], v[70:71]
	v_pk_add_f32 v[22:23], v[94:95], 1.0 op_sel_hi:[1,0]
	v_pk_mul_f32 v[16:17], v[16:17], v[72:73]
	v_pk_add_f32 v[24:25], v[96:97], 1.0 op_sel_hi:[1,0]
	v_pk_fma_f32 v[14:15], v[14:15], v[22:23], v[82:83]
	v_pk_fma_f32 v[16:17], v[16:17], v[24:25], v[84:85]
	v_cvt_pk_bf16_f32 v14, v14, v15
	s_nop 0
	v_cvt_pk_bf16_f32 v15, v16, v17
	global_store_dwordx2 v[50:51], v[14:15], off offset:1024
	s_cbranch_vccnz .LBB0_173
	v_mov_b32_e32 v26, v52
	v_mov_b32_e32 v27, v52
	v_pk_mul_f32 v[12:13], v[12:13], v[26:27]
	v_pk_mul_f32 v[10:11], v[10:11], v[52:53]
	v_pk_mul_f32 v[12:13], v[12:13], v[72:73]
	v_pk_mul_f32 v[10:11], v[10:11], v[70:71]
	s_waitcnt vmcnt(10)
	v_pk_add_f32 v[20:21], v[130:131], 1.0 op_sel_hi:[1,0]
	v_pk_add_f32 v[18:19], v[132:133], 1.0 op_sel_hi:[1,0]
	v_pk_fma_f32 v[10:11], v[10:11], v[20:21], v[114:115]
	v_pk_fma_f32 v[12:13], v[12:13], v[18:19], v[116:117]
	v_cvt_pk_bf16_f32 v10, v10, v11
	s_nop 0
	v_cvt_pk_bf16_f32 v11, v12, v13
	global_store_dwordx2 v[30:31], v[10:11], off offset:1024
.LBB0_173:
	v_mov_b32_e32 v22, v54
	v_mov_b32_e32 v23, v54
	v_pk_mul_f32 v[6:7], v[6:7], v[54:55]
	v_pk_mul_f32 v[8:9], v[8:9], v[22:23]
	s_and_b64 vcc, exec, s[40:41]
	s_waitcnt vmcnt(5)
	v_pk_mul_f32 v[6:7], v[6:7], v[74:75]
	v_pk_add_f32 v[14:15], v[98:99], 1.0 op_sel_hi:[1,0]
	v_pk_mul_f32 v[8:9], v[8:9], v[76:77]
	v_pk_add_f32 v[16:17], v[100:101], 1.0 op_sel_hi:[1,0]
	v_pk_fma_f32 v[6:7], v[6:7], v[14:15], v[86:87]
	v_pk_fma_f32 v[8:9], v[8:9], v[16:17], v[88:89]
	v_cvt_pk_bf16_f32 v6, v6, v7
	s_nop 0
	v_cvt_pk_bf16_f32 v7, v8, v9
	global_store_dwordx2 v[50:51], v[6:7], off offset:1536
	s_cbranch_vccnz .LBB0_162
	v_mov_b32_e32 v18, v52
	v_mov_b32_e32 v19, v52
	v_pk_mul_f32 v[2:3], v[2:3], v[52:53]
	v_pk_mul_f32 v[4:5], v[4:5], v[18:19]
	v_pk_mul_f32 v[2:3], v[2:3], v[74:75]
	v_pk_mul_f32 v[4:5], v[4:5], v[76:77]
	s_waitcnt vmcnt(7)
	v_pk_add_f32 v[6:7], v[134:135], 1.0 op_sel_hi:[1,0]
	v_pk_add_f32 v[8:9], v[136:137], 1.0 op_sel_hi:[1,0]
	v_pk_fma_f32 v[2:3], v[2:3], v[6:7], v[118:119]
	v_pk_fma_f32 v[4:5], v[4:5], v[8:9], v[120:121]
	v_cvt_pk_bf16_f32 v2, v2, v3
	s_nop 0
	v_cvt_pk_bf16_f32 v3, v4, v5
	global_store_dwordx2 v[30:31], v[2:3], off offset:1536
	s_branch .LBB0_162
